# v36 + spatial-gating epilogue: counted vmcnt(30) per element instead of one full drain
# baseline (speedup 1.0000x reference)
; DI unsigned pk2(float lo, float hi) { f32x2 v = {lo, hi}; bf16x2_t b = __builtin_convertvector(v, bf16x2_t); return __builtin_bit_cast(unsigned, b); }
; DI float bf2f(unsigned short u) { return __uint_as_float(((unsigned)u) << 16); }
; DI int crow(int i, int h) { return (i & 3) + 8 * (i >> 2) + 4 * h; }
; DI void phase_sgu(ArgsP AP, LAS unsigned char* lds) {
;     ...
; #pragma unroll
;             for (int ci = 0; ci < 2; ++ci)
; #pragma unroll
;                 for (int i = 0; i < 16; ++i) { const int t = 32 * tb + crow(i, h), c = g * 128 + 32 * (cb0 + ci) + r32; const size_t row = r0 + t;
;                     const float mixed = acc[ci][i] + gbs[g * 128 + t]; const float uv = bf2f(UV[row * 2048 + c]);
;                     OA[row * DM + c] = (bf16)(pk2(uv * mixed, 0.f) & 0xffffu); }
.LBB0_221:
	v_add_u32_e32 v32, s2, v40
	v_or_b32_e32 v87, s2, v154
	v_ashrrev_i32_e32 v33, 31, v32
	v_lshl_add_u64 v[146:147], v[32:33], 2, s[46:47]
	v_or_b32_e32 v32, s9, v87
	v_lshlrev_b32_e32 v96, 1, v32
	global_load_dwordx4 v[130:133], v[146:147], off
	global_load_dwordx4 v[134:137], v[146:147], off offset:32
	global_load_dwordx4 v[138:141], v[146:147], off offset:64
	global_load_dwordx4 v[142:145], v[146:147], off offset:96
	v_lshl_add_u64 v[150:151], s[0:1], 0, v[96:97]
	v_lshl_add_u64 v[152:153], s[16:17], 0, v[96:97]
	v_lshl_add_u64 v[148:149], s[22:23], 0, v[40:41]
	v_lshlrev_b64 v[148:149], 12, v[148:149]
	v_lshl_add_u64 v[148:149], v[150:151], 0, v[148:149]
	global_load_ushort v98, v[148:149], off
	global_load_ushort v99, v[148:149], off offset:64
	v_lshl_add_u64 v[148:149], s[22:23], 0, v[50:51]
	v_lshlrev_b64 v[148:149], 12, v[148:149]
	v_lshl_add_u64 v[148:149], v[150:151], 0, v[148:149]
	global_load_ushort v100, v[148:149], off
	global_load_ushort v101, v[148:149], off offset:64
	v_lshl_add_u64 v[148:149], s[22:23], 0, v[52:53]
	v_lshlrev_b64 v[148:149], 12, v[148:149]
	v_lshl_add_u64 v[148:149], v[150:151], 0, v[148:149]
	global_load_ushort v102, v[148:149], off
	global_load_ushort v103, v[148:149], off offset:64
	v_lshl_add_u64 v[148:149], s[22:23], 0, v[54:55]
	v_lshlrev_b64 v[148:149], 12, v[148:149]
	v_lshl_add_u64 v[148:149], v[150:151], 0, v[148:149]
	global_load_ushort v104, v[148:149], off
	global_load_ushort v105, v[148:149], off offset:64
	v_lshl_add_u64 v[148:149], s[22:23], 0, v[56:57]
	v_lshlrev_b64 v[148:149], 12, v[148:149]
	v_lshl_add_u64 v[148:149], v[150:151], 0, v[148:149]
	global_load_ushort v106, v[148:149], off
	global_load_ushort v107, v[148:149], off offset:64
	v_lshl_add_u64 v[148:149], s[22:23], 0, v[58:59]
	v_lshlrev_b64 v[148:149], 12, v[148:149]
	v_lshl_add_u64 v[148:149], v[150:151], 0, v[148:149]
	global_load_ushort v108, v[148:149], off
	global_load_ushort v109, v[148:149], off offset:64
	v_lshl_add_u64 v[148:149], s[22:23], 0, v[60:61]
	v_lshlrev_b64 v[148:149], 12, v[148:149]
	v_lshl_add_u64 v[148:149], v[150:151], 0, v[148:149]
	global_load_ushort v110, v[148:149], off
	global_load_ushort v111, v[148:149], off offset:64
	v_lshl_add_u64 v[148:149], s[22:23], 0, v[62:63]
	v_lshlrev_b64 v[148:149], 12, v[148:149]
	v_lshl_add_u64 v[148:149], v[150:151], 0, v[148:149]
	global_load_ushort v112, v[148:149], off
	global_load_ushort v113, v[148:149], off offset:64
	v_lshl_add_u64 v[148:149], s[22:23], 0, v[64:65]
	v_lshlrev_b64 v[148:149], 12, v[148:149]
	v_lshl_add_u64 v[148:149], v[150:151], 0, v[148:149]
	global_load_ushort v114, v[148:149], off
	global_load_ushort v115, v[148:149], off offset:64
	v_lshl_add_u64 v[148:149], s[22:23], 0, v[66:67]
	v_lshlrev_b64 v[148:149], 12, v[148:149]
	v_lshl_add_u64 v[148:149], v[150:151], 0, v[148:149]
	global_load_ushort v116, v[148:149], off
	global_load_ushort v117, v[148:149], off offset:64
	v_lshl_add_u64 v[148:149], s[22:23], 0, v[68:69]
	v_lshlrev_b64 v[148:149], 12, v[148:149]
	v_lshl_add_u64 v[148:149], v[150:151], 0, v[148:149]
	global_load_ushort v118, v[148:149], off
	global_load_ushort v119, v[148:149], off offset:64
	v_lshl_add_u64 v[148:149], s[22:23], 0, v[70:71]
	v_lshlrev_b64 v[148:149], 12, v[148:149]
	v_lshl_add_u64 v[148:149], v[150:151], 0, v[148:149]
	global_load_ushort v120, v[148:149], off
	global_load_ushort v121, v[148:149], off offset:64
	v_lshl_add_u64 v[148:149], s[22:23], 0, v[72:73]
	v_lshlrev_b64 v[148:149], 12, v[148:149]
	v_lshl_add_u64 v[148:149], v[150:151], 0, v[148:149]
	global_load_ushort v122, v[148:149], off
	global_load_ushort v123, v[148:149], off offset:64
	v_lshl_add_u64 v[148:149], s[22:23], 0, v[74:75]
	v_lshlrev_b64 v[148:149], 12, v[148:149]
	v_lshl_add_u64 v[148:149], v[150:151], 0, v[148:149]
	global_load_ushort v124, v[148:149], off
	global_load_ushort v125, v[148:149], off offset:64
	v_lshl_add_u64 v[148:149], s[22:23], 0, v[76:77]
	v_lshlrev_b64 v[148:149], 12, v[148:149]
	v_lshl_add_u64 v[148:149], v[150:151], 0, v[148:149]
	global_load_ushort v126, v[148:149], off
	global_load_ushort v127, v[148:149], off offset:64
	v_lshl_add_u64 v[148:149], s[22:23], 0, v[78:79]
	v_lshlrev_b64 v[148:149], 12, v[148:149]
	v_lshl_add_u64 v[148:149], v[150:151], 0, v[148:149]
	global_load_ushort v128, v[148:149], off
	global_load_ushort v129, v[148:149], off offset:64
	s_waitcnt vmcnt(30)
	v_lshl_add_u64 v[148:149], s[22:23], 0, v[40:41]
	v_lshlrev_b64 v[148:149], 11, v[148:149]
	v_lshl_add_u64 v[148:149], v[152:153], 0, v[148:149]
	v_add_f32_e32 v32, v16, v130
	v_lshlrev_b32_e32 v34, 16, v98
	v_mul_f32_e32 v32, v32, v34
	v_cvt_pk_bf16_f32 v32, v32, s0
	global_store_short v[148:149], v32, off
	v_add_f32_e32 v33, v0, v130
	v_lshlrev_b32_e32 v35, 16, v99
	v_mul_f32_e32 v33, v33, v35
	v_cvt_pk_bf16_f32 v33, v33, s0
	global_store_short v[148:149], v33, off offset:64
	s_waitcnt vmcnt(30)
	v_lshl_add_u64 v[148:149], s[22:23], 0, v[50:51]
	v_lshlrev_b64 v[148:149], 11, v[148:149]
	v_lshl_add_u64 v[148:149], v[152:153], 0, v[148:149]
	v_add_f32_e32 v32, v17, v131
	v_lshlrev_b32_e32 v34, 16, v100
	v_mul_f32_e32 v32, v32, v34
	v_cvt_pk_bf16_f32 v32, v32, s0
	global_store_short v[148:149], v32, off
	v_add_f32_e32 v33, v1, v131
	v_lshlrev_b32_e32 v35, 16, v101
	v_mul_f32_e32 v33, v33, v35
	v_cvt_pk_bf16_f32 v33, v33, s0
	global_store_short v[148:149], v33, off offset:64
	s_waitcnt vmcnt(30)
; DI unsigned pk2(float lo, float hi) { f32x2 v = {lo, hi}; bf16x2_t b = __builtin_convertvector(v, bf16x2_t); return __builtin_bit_cast(unsigned, b); }
; DI float bf2f(unsigned short u) { return __uint_as_float(((unsigned)u) << 16); }
; DI int crow(int i, int h) { return (i & 3) + 8 * (i >> 2) + 4 * h; }
; DI void phase_sgu(ArgsP AP, LAS unsigned char* lds) {
;     ...
;                 for (int i = 0; i < 16; ++i) { const int t = 32 * tb + crow(i, h), c = g * 128 + 32 * (cb0 + ci) + r32; const size_t row = r0 + t;
;                     const float mixed = acc[ci][i] + gbs[g * 128 + t]; const float uv = bf2f(UV[row * 2048 + c]);
;                     OA[row * DM + c] = (bf16)(pk2(uv * mixed, 0.f) & 0xffffu); }
	v_lshl_add_u64 v[148:149], s[22:23], 0, v[52:53]
	v_lshlrev_b64 v[148:149], 11, v[148:149]
	v_lshl_add_u64 v[148:149], v[152:153], 0, v[148:149]
	v_add_f32_e32 v32, v18, v132
	v_lshlrev_b32_e32 v34, 16, v102
	v_mul_f32_e32 v32, v32, v34
	v_cvt_pk_bf16_f32 v32, v32, s0
	global_store_short v[148:149], v32, off
	v_add_f32_e32 v33, v2, v132
	v_lshlrev_b32_e32 v35, 16, v103
	v_mul_f32_e32 v33, v33, v35
	v_cvt_pk_bf16_f32 v33, v33, s0
	global_store_short v[148:149], v33, off offset:64
	s_waitcnt vmcnt(30)
	v_lshl_add_u64 v[148:149], s[22:23], 0, v[54:55]
	v_lshlrev_b64 v[148:149], 11, v[148:149]
	v_lshl_add_u64 v[148:149], v[152:153], 0, v[148:149]
	v_add_f32_e32 v32, v19, v133
	v_lshlrev_b32_e32 v34, 16, v104
	v_mul_f32_e32 v32, v32, v34
	v_cvt_pk_bf16_f32 v32, v32, s0
	global_store_short v[148:149], v32, off
	v_add_f32_e32 v33, v3, v133
	v_lshlrev_b32_e32 v35, 16, v105
	v_mul_f32_e32 v33, v33, v35
	v_cvt_pk_bf16_f32 v33, v33, s0
	global_store_short v[148:149], v33, off offset:64
	s_waitcnt vmcnt(30)
	v_lshl_add_u64 v[148:149], s[22:23], 0, v[56:57]
	v_lshlrev_b64 v[148:149], 11, v[148:149]
	v_lshl_add_u64 v[148:149], v[152:153], 0, v[148:149]
	v_add_f32_e32 v32, v20, v134
	v_lshlrev_b32_e32 v34, 16, v106
	v_mul_f32_e32 v32, v32, v34
	v_cvt_pk_bf16_f32 v32, v32, s0
	global_store_short v[148:149], v32, off
	v_add_f32_e32 v33, v4, v134
	v_lshlrev_b32_e32 v35, 16, v107
	v_mul_f32_e32 v33, v33, v35
	v_cvt_pk_bf16_f32 v33, v33, s0
	global_store_short v[148:149], v33, off offset:64
	s_waitcnt vmcnt(30)
	v_lshl_add_u64 v[148:149], s[22:23], 0, v[58:59]
	v_lshlrev_b64 v[148:149], 11, v[148:149]
	v_lshl_add_u64 v[148:149], v[152:153], 0, v[148:149]
	v_add_f32_e32 v32, v21, v135
	v_lshlrev_b32_e32 v34, 16, v108
	v_mul_f32_e32 v32, v32, v34
	v_cvt_pk_bf16_f32 v32, v32, s0
	global_store_short v[148:149], v32, off
	v_add_f32_e32 v33, v5, v135
	v_lshlrev_b32_e32 v35, 16, v109
	v_mul_f32_e32 v33, v33, v35
	v_cvt_pk_bf16_f32 v33, v33, s0
	global_store_short v[148:149], v33, off offset:64
	s_waitcnt vmcnt(30)
	v_lshl_add_u64 v[148:149], s[22:23], 0, v[60:61]
	v_lshlrev_b64 v[148:149], 11, v[148:149]
	v_lshl_add_u64 v[148:149], v[152:153], 0, v[148:149]
	v_add_f32_e32 v32, v22, v136
	v_lshlrev_b32_e32 v34, 16, v110
	v_mul_f32_e32 v32, v32, v34
	v_cvt_pk_bf16_f32 v32, v32, s0
	global_store_short v[148:149], v32, off
	v_add_f32_e32 v33, v6, v136
	v_lshlrev_b32_e32 v35, 16, v111
	v_mul_f32_e32 v33, v33, v35
	v_cvt_pk_bf16_f32 v33, v33, s0
	global_store_short v[148:149], v33, off offset:64
	s_waitcnt vmcnt(30)
	v_lshl_add_u64 v[148:149], s[22:23], 0, v[62:63]
	v_lshlrev_b64 v[148:149], 11, v[148:149]
	v_lshl_add_u64 v[148:149], v[152:153], 0, v[148:149]
	v_add_f32_e32 v32, v23, v137
	v_lshlrev_b32_e32 v34, 16, v112
	v_mul_f32_e32 v32, v32, v34
	v_cvt_pk_bf16_f32 v32, v32, s0
	global_store_short v[148:149], v32, off
	v_add_f32_e32 v33, v7, v137
	v_lshlrev_b32_e32 v35, 16, v113
	v_mul_f32_e32 v33, v33, v35
	v_cvt_pk_bf16_f32 v33, v33, s0
	global_store_short v[148:149], v33, off offset:64
	s_waitcnt vmcnt(30)
	v_lshl_add_u64 v[148:149], s[22:23], 0, v[64:65]
	v_lshlrev_b64 v[148:149], 11, v[148:149]
	v_lshl_add_u64 v[148:149], v[152:153], 0, v[148:149]
	v_add_f32_e32 v32, v24, v138
	v_lshlrev_b32_e32 v34, 16, v114
	v_mul_f32_e32 v32, v32, v34
	v_cvt_pk_bf16_f32 v32, v32, s0
	global_store_short v[148:149], v32, off
	v_add_f32_e32 v33, v8, v138
	v_lshlrev_b32_e32 v35, 16, v115
	v_mul_f32_e32 v33, v33, v35
	v_cvt_pk_bf16_f32 v33, v33, s0
	global_store_short v[148:149], v33, off offset:64
	s_waitcnt vmcnt(30)
; DI unsigned pk2(float lo, float hi) { f32x2 v = {lo, hi}; bf16x2_t b = __builtin_convertvector(v, bf16x2_t); return __builtin_bit_cast(unsigned, b); }
; DI float bf2f(unsigned short u) { return __uint_as_float(((unsigned)u) << 16); }
; DI int crow(int i, int h) { return (i & 3) + 8 * (i >> 2) + 4 * h; }
; DI void phase_sgu(ArgsP AP, LAS unsigned char* lds) {
;     ...
;                 for (int i = 0; i < 16; ++i) { const int t = 32 * tb + crow(i, h), c = g * 128 + 32 * (cb0 + ci) + r32; const size_t row = r0 + t;
;                     const float mixed = acc[ci][i] + gbs[g * 128 + t]; const float uv = bf2f(UV[row * 2048 + c]);
;                     OA[row * DM + c] = (bf16)(pk2(uv * mixed, 0.f) & 0xffffu); }
;             __syncthreads();
	v_lshl_add_u64 v[148:149], s[22:23], 0, v[66:67]
	v_lshlrev_b64 v[148:149], 11, v[148:149]
	v_lshl_add_u64 v[148:149], v[152:153], 0, v[148:149]
	v_add_f32_e32 v32, v25, v139
	v_lshlrev_b32_e32 v34, 16, v116
	v_mul_f32_e32 v32, v32, v34
	v_cvt_pk_bf16_f32 v32, v32, s0
	global_store_short v[148:149], v32, off
	v_add_f32_e32 v33, v9, v139
	v_lshlrev_b32_e32 v35, 16, v117
	v_mul_f32_e32 v33, v33, v35
	v_cvt_pk_bf16_f32 v33, v33, s0
	global_store_short v[148:149], v33, off offset:64
	s_waitcnt vmcnt(30)
	v_lshl_add_u64 v[148:149], s[22:23], 0, v[68:69]
	v_lshlrev_b64 v[148:149], 11, v[148:149]
	v_lshl_add_u64 v[148:149], v[152:153], 0, v[148:149]
	v_add_f32_e32 v32, v26, v140
	v_lshlrev_b32_e32 v34, 16, v118
	v_mul_f32_e32 v32, v32, v34
	v_cvt_pk_bf16_f32 v32, v32, s0
	global_store_short v[148:149], v32, off
	v_add_f32_e32 v33, v10, v140
	v_lshlrev_b32_e32 v35, 16, v119
	v_mul_f32_e32 v33, v33, v35
	v_cvt_pk_bf16_f32 v33, v33, s0
	global_store_short v[148:149], v33, off offset:64
	s_waitcnt vmcnt(30)
	v_lshl_add_u64 v[148:149], s[22:23], 0, v[70:71]
	v_lshlrev_b64 v[148:149], 11, v[148:149]
	v_lshl_add_u64 v[148:149], v[152:153], 0, v[148:149]
	v_add_f32_e32 v32, v27, v141
	v_lshlrev_b32_e32 v34, 16, v120
	v_mul_f32_e32 v32, v32, v34
	v_cvt_pk_bf16_f32 v32, v32, s0
	global_store_short v[148:149], v32, off
	v_add_f32_e32 v33, v11, v141
	v_lshlrev_b32_e32 v35, 16, v121
	v_mul_f32_e32 v33, v33, v35
	v_cvt_pk_bf16_f32 v33, v33, s0
	global_store_short v[148:149], v33, off offset:64
	s_waitcnt vmcnt(30)
	v_lshl_add_u64 v[148:149], s[22:23], 0, v[72:73]
	v_lshlrev_b64 v[148:149], 11, v[148:149]
	v_lshl_add_u64 v[148:149], v[152:153], 0, v[148:149]
	v_add_f32_e32 v32, v28, v142
	v_lshlrev_b32_e32 v34, 16, v122
	v_mul_f32_e32 v32, v32, v34
	v_cvt_pk_bf16_f32 v32, v32, s0
	global_store_short v[148:149], v32, off
	v_add_f32_e32 v33, v12, v142
	v_lshlrev_b32_e32 v35, 16, v123
	v_mul_f32_e32 v33, v33, v35
	v_cvt_pk_bf16_f32 v33, v33, s0
	global_store_short v[148:149], v33, off offset:64
	s_waitcnt vmcnt(30)
	v_lshl_add_u64 v[148:149], s[22:23], 0, v[74:75]
	v_lshlrev_b64 v[148:149], 11, v[148:149]
	v_lshl_add_u64 v[148:149], v[152:153], 0, v[148:149]
	v_add_f32_e32 v32, v29, v143
	v_lshlrev_b32_e32 v34, 16, v124
	v_mul_f32_e32 v32, v32, v34
	v_cvt_pk_bf16_f32 v32, v32, s0
	global_store_short v[148:149], v32, off
	v_add_f32_e32 v33, v13, v143
	v_lshlrev_b32_e32 v35, 16, v125
	v_mul_f32_e32 v33, v33, v35
	v_cvt_pk_bf16_f32 v33, v33, s0
	global_store_short v[148:149], v33, off offset:64
	s_waitcnt vmcnt(30)
	v_lshl_add_u64 v[148:149], s[22:23], 0, v[76:77]
	v_lshlrev_b64 v[148:149], 11, v[148:149]
	v_lshl_add_u64 v[148:149], v[152:153], 0, v[148:149]
	v_add_f32_e32 v32, v30, v144
	v_lshlrev_b32_e32 v34, 16, v126
	v_mul_f32_e32 v32, v32, v34
	v_cvt_pk_bf16_f32 v32, v32, s0
	global_store_short v[148:149], v32, off
	v_add_f32_e32 v33, v14, v144
	v_lshlrev_b32_e32 v35, 16, v127
	v_mul_f32_e32 v33, v33, v35
	v_cvt_pk_bf16_f32 v33, v33, s0
	global_store_short v[148:149], v33, off offset:64
	s_waitcnt vmcnt(30)
	v_lshl_add_u64 v[148:149], s[22:23], 0, v[78:79]
	v_lshlrev_b64 v[148:149], 11, v[148:149]
	v_lshl_add_u64 v[148:149], v[152:153], 0, v[148:149]
	v_add_f32_e32 v32, v31, v145
	v_lshlrev_b32_e32 v34, 16, v128
	v_mul_f32_e32 v32, v32, v34
	v_cvt_pk_bf16_f32 v32, v32, s0
	global_store_short v[148:149], v32, off
	v_add_f32_e32 v33, v15, v145
	v_lshlrev_b32_e32 v35, 16, v129
	v_mul_f32_e32 v33, v33, v35
	v_cvt_pk_bf16_f32 v33, v33, s0
	global_store_short v[148:149], v33, off offset:64
	s_barrier
